# entry grid sync: dropped the per-workgroup L2 write-back at arrival (only workgroup 0 has stores to release, and it already writes them back itself)
# speedup vs baseline: 1.0074x; 1.0061x over previous
; #define LAS __attribute__((address_space(3)))
; __global__ void __launch_bounds__(512, 2) fwd_megakernel(Params p) {
;     extern __shared__ __attribute__((aligned(16))) unsigned char shm[];
;     cg::grid_group grid = cg::this_grid();
;     LAS unsigned char* lds = (LAS unsigned char*)shm;
;     bf16_t* XN = (bf16_t*)(p.ws + W_XN); bf16_t* PROJ = (bf16_t*)(p.ws + W_PROJ); bf16_t* A2 = (bf16_t*)(p.ws + W_A2);
;     volatile LAS unsigned* xst = (volatile LAS unsigned*)(lds + LDS_BYTES - 16);
;     if (threadIdx.x == 0) { xst[0] = 0u; xst[1] = 0u; }
;     __syncthreads();
;     if (blockIdx.x == 0 && threadIdx.x < 64) {
;         unsigned* bw = (unsigned*)(p.ws + W_BAR);
;         for (int i = threadIdx.x; i < 4096; i += 64) __hip_atomic_store(bw + i, 0u, __ATOMIC_RELAXED, __HIP_MEMORY_SCOPE_AGENT);
;         asm volatile("s_waitcnt vmcnt(0)" ::: "memory");
;         __builtin_amdgcn_fence(__ATOMIC_RELEASE, "agent");
;         asm volatile("s_waitcnt vmcnt(0)" ::: "memory");
;     }
;     grid.sync();
.LBB0_6:
	s_or_b64 exec, exec, s[6:7]
	s_load_dwordx16 s[8:23], s[0:1], 0x0
	v_lshrrev_b32_e32 v1, 20, v0
	v_lshrrev_b32_e32 v0, 10, v0
	v_or_b32_e32 v0, v0, v1
	s_waitcnt lgkmcnt(0)
	v_writelane_b32 v244, s8, 12
	s_barrier
	s_nop 0
	v_writelane_b32 v244, s9, 13
	v_writelane_b32 v244, s10, 14
	v_writelane_b32 v244, s11, 15
	v_writelane_b32 v244, s12, 16
	v_writelane_b32 v244, s13, 17
	v_writelane_b32 v244, s14, 18
	v_writelane_b32 v244, s15, 19
	v_writelane_b32 v244, s16, 20
	v_writelane_b32 v244, s17, 21
	v_writelane_b32 v244, s18, 22
	v_writelane_b32 v244, s19, 23
	v_writelane_b32 v244, s20, 24
	v_writelane_b32 v244, s21, 25
	v_writelane_b32 v244, s22, 26
	v_writelane_b32 v244, s23, 27
	s_load_dwordx16 s[12:27], s[0:1], 0x40
	s_movk_i32 s0, 0x3ff
	v_and_or_b32 v0, v0, s0, v192
	v_cmp_eq_u32_e32 vcc, 0, v0
	s_and_saveexec_b64 s[0:1], vcc
	s_cbranch_execz .LBB0_16
	s_waitcnt lgkmcnt(0)
	s_nop 0
	s_load_dwordx2 s[4:5], s[4:5], 0x58
	v_mov_b32_e32 v2, 0
	s_mov_b64 s[2:3], exec
	v_mbcnt_lo_u32_b32 v1, s2, 0
	v_mbcnt_hi_u32_b32 v1, s3, v1
	s_waitcnt lgkmcnt(0)
	global_load_dword v0, v2, s[4:5] offset:40
	v_cmp_eq_u32_e32 vcc, 0, v1
	s_and_saveexec_b64 s[6:7], vcc
	s_cbranch_execz .LBB0_9
	s_bcnt1_i32_b64 s2, s[2:3]
	v_mov_b32_e32 v3, s2
	global_atomic_add v3, v2, v3, s[4:5] offset:32 sc0
